# lean8 = lean7 + W_in gate-bias floats loaded once per phase into spare VGPRs (16 load+vmcnt(0) pairs per gate tile removed)
# speedup vs baseline: 1.0036x; 1.0036x over previous
; #define PG8_STAGE(bufoff, gbase, voff) do { _Pragma("unroll") for (int _i = 0; _i < 2; ++_i) \
;         __builtin_amdgcn_global_load_lds((const unsigned*)((const char*)(gbase) + (voff)[_i]), (PG8_LAS unsigned*)(lds + (bufoff) + ldsw + _i * 8192), 16, 0, 0); } while (0)
; #define PG8_WAIT_V(n) asm volatile("s_waitcnt vmcnt(" #n ")" ::: "memory")
; #define PG8_BAR __builtin_amdgcn_s_barrier()
;     __device__ void init(int M, int N, int G_, int c_) { base.init(M, N, G_, c_); }
; #define P_IN(i) ((const float*)rd_ptr(i))
; template <class Epi, class Sched, bool ALIGN_EPI = false, bool SP2 = false>
; __device__ __forceinline__ void gemm_phase(PG8_LAS unsigned char* lds, const Gemm g, const Sched& S, const Epi& E) {
;     ...
;         PG8_STAGE(PG8_SB(0, 0), cB, voffB); PG8_STAGE(PG8_SB(0, 1), cB + hstep, voffB); PG8_STAGE(PG8_SA(0, 0), cA, voffA); PG8_STAGE(PG8_SA(0, 1), cA + hstep, voffA);
;         if (wr == 1) PG8_BAR;
;         PG8_WAIT_V(2); PG8_BAR;
;         PG8_STAGE(PG8_SB(1, 0), cB + kstep, voffB); PG8_STAGE(PG8_SA(1, 0), cA + kstep, voffA); PG8_STAGE(PG8_SB(1, 1), cB + hstep + kstep, voffB);
;         PG8_WAIT_V(6); PG8_BAR;
; __global__ void __launch_bounds__(NTHR, 2) trunk_fwd(Args args) {
;     ...
;             pg8::Gemm g{(const u16*)(ws + WS_XB) + hrow * DM, (const u16*)(wl + WO_IN), MH, 24 * 256, DM}; pg8::StaticOrder S; S.init(MH, 24 * 256, G, bx);
;             pg8::EpiWin E{(u16*)(ws + WS_ZA), (u16*)(ws + WS_QC), (u16*)(ws + WS_KC), (u16*)(ws + WS_VC), (float*)(ws + WS_MIF), (const float*)(ws + WS_SSP) + hrow * 16, (const float*)(ws + WS_COS) + hrow * 32, (const float*)(ws + WS_SIN) + hrow * 32, P_IN(11) + l * 8};
.LBB0_1124:
	s_add_u32 s12, s62, 0xa400000
	s_addc_u32 s13, s63, 0
	s_add_u32 s28, s62, 0x17400000
	s_addc_u32 s52, s63, 0
	s_add_u32 s54, s62, 0x18400000
	s_addc_u32 s41, s63, 0
	s_add_u32 s14, s62, 0x1dc00000
	v_readlane_b32 s18, v255, 13
	s_addc_u32 s15, s63, 0
	s_lshl_b32 s1, s18, 6
	s_add_u32 s1, s62, s1
	s_addc_u32 s5, s63, 0
	s_add_u32 s16, s1, 0x1e500000
	s_addc_u32 s17, s5, 0
	s_lshl_b32 s1, s18, 7
	s_add_u32 s1, s62, s1
	s_addc_u32 s5, s63, 0
	v_readlane_b32 s19, v255, 14
	s_add_u32 s18, s1, 0x1dd00000
	s_addc_u32 s19, s5, 0
	s_add_u32 s20, s1, 0x1e100000
	s_addc_u32 s21, s5, 0
	s_lshl_b32 s30, s78, 3
	s_lshl_b64 s[50:51], s[30:31], 2
	s_add_u32 s66, s22, s50
	s_addc_u32 s67, s3, s51
	s_and_b32 s51, s23, 3
	s_lshl_b32 s1, s0, 6
	s_lshl_b32 s3, s0, 13
	s_lshl_b32 s68, s51, 5
	s_lshl_b32 s5, s51, 12
	global_load_dwordx4 v[222:225], v221, s[66:67]
	global_load_dwordx4 v[226:229], v221, s[66:67] offset:16
	s_add_u32 s0, s10, 0x8000
	v_mov_b32_e32 v171, v221
	v_writelane_b32 v255, s1, 18
	s_addc_u32 s1, s11, 0
	s_add_i32 m0, s33, 0x18000
	v_lshl_add_u64 v[8:9], s[0:1], 0, v[170:171]
	v_mov_b32_e32 v175, v221
	s_waitcnt vmcnt(2)
	s_barrier
	global_load_lds_dwordx4 v[8:9], off
	s_add_i32 m0, s33, 0x1a000
	v_lshl_add_u64 v[8:9], s[0:1], 0, v[174:175]
	s_add_u32 s0, s6, 0x8000
	v_mov_b32_e32 v169, v221
	s_addc_u32 s1, s7, 0
	s_add_i32 s53, s33, 0x8000
	v_mov_b32_e32 v173, v221
	global_load_lds_dwordx4 v[8:9], off
	s_mov_b32 m0, s53
	s_add_i32 s27, s33, 0xa000
	global_load_lds_dwordx4 v168, s[0:1]
	v_lshl_add_u64 v[8:9], s[0:1], 0, v[172:173]
	s_add_u32 s0, s10, 0xc000
	s_mov_b32 m0, s27
	s_addc_u32 s1, s11, 0
	global_load_lds_dwordx4 v[8:9], off
	s_add_i32 m0, s33, 0x1c000
	s_nop 0
	global_load_lds_dwordx4 v170, s[0:1]
	s_add_i32 m0, s33, 0x1e000
	v_and_b32_e32 v7, 48, v0
	global_load_lds_dwordx4 v174, s[0:1]
	v_lshlrev_b32_e32 v8, 6, v0
	s_movk_i32 s0, 0x3c0
	v_lshlrev_b32_e32 v0, 2, v0
	s_cmpk_lt_u32 s2, 0x100
	v_and_or_b32 v7, v8, s0, v7
	v_and_b32_e32 v0, 32, v0
	s_cselect_b64 s[70:71], -1, 0
	s_lshl_b32 s0, s23, 11
	v_bitop3_b32 v8, v7, s3, v0 bitop3:0xde
	v_bitop3_b32 v192, v7, s5, v0 bitop3:0xde
	s_and_b32 s0, s0, 0x1000
	v_lshlrev_b32_e32 v0, 10, v1
	s_or_b32 s0, s0, 0xfffdc000
	v_and_b32_e32 v0, 0xfffff800, v0
	s_cmp_eq_u32 s51, 0
	v_lshl_add_u32 v0, v2, 7, v0
	v_and_b32_e32 v1, 1, v1
	s_cselect_b64 s[72:73], -1, 0
	s_lshl_b32 s2, s23, 6
	v_lshl_or_b32 v0, v1, 6, v0
	s_ashr_i32 s39, s60, 31
	s_ashr_i32 s50, s58, 31
	s_and_b32 s2, s2, 64
	v_lshl_add_u32 v176, v3, 1, v0
	v_lshlrev_b32_e32 v0, 10, v4
	s_add_u32 s2, s62, s2
	v_and_b32_e32 v0, 0xfffff800, v0
	s_waitcnt vmcnt(6)
	s_addc_u32 s3, s63, 0
	v_lshl_add_u32 v0, v5, 7, v0
	v_and_b32_e32 v1, 1, v4
	s_add_u32 s74, s2, 0x19400000
	v_lshl_or_b32 v0, v1, 6, v0
	s_mov_b32 s69, s31
	s_mov_b32 s1, 0
	s_addc_u32 s75, s3, 0
	v_mov_b32_e32 v177, v221
	v_lshl_add_u32 v178, v6, 1, v0
	v_mov_b32_e32 v179, v221
	v_add_u32_e32 v193, 0, v8
	s_barrier
	s_branch .LBB0_1127

;     __device__ __forceinline__ void operator()(const f32x4 (&acc)[2][2][4][2], const Unit& u, int wr, int wc, int, int) const {
;     ...
;                     if (wc == 0 && fq == 0) {
;                         float* mo = mif + (size_t)row * 8;
;                         *(v4f*)(mo) = (v4f){v0[0] + gate_b[0], v0[1] + gate_b[1], v0[2] + gate_b[2], v0[3] + gate_b[3]};
;                         *(v4f*)(mo + 4) = (v4f){v0[4] + gate_b[4], v0[5] + gate_b[5], v0[6] + gate_b[6], v0[7] + gate_b[7]};
;                     }
.LBB0_1148:
	s_andn2_b64 vcc, exec, s[10:11]
	s_cbranch_vccnz .LBB0_1152
	s_and_saveexec_b64 s[10:11], s[84:85]
	s_cbranch_execz .LBB0_1151
	s_nop 1
	v_lshlrev_b64 v[144:145], 5, v[180:181]
	v_lshl_add_u64 v[144:145], s[14:15], 0, v[144:145]
	v_pk_add_f32 v[196:197], v[166:167], v[222:223]
	v_pk_add_f32 v[198:199], v[158:159], v[224:225]
	global_store_dwordx4 v[144:145], v[196:199], off
	s_nop 1
	v_pk_add_f32 v[196:197], v[152:153], v[226:227]
	v_pk_add_f32 v[198:199], v[148:149], v[228:229]
	global_store_dwordx4 v[144:145], v[196:199], off offset:16

;     __device__ __forceinline__ void operator()(const f32x4 (&acc)[2][2][4][2], const Unit& u, int wr, int wc, int, int) const {
;     ...
;                     if (wc == 0 && fq == 0) {
;                         float* mo = mif + (size_t)row * 8;
;                         *(v4f*)(mo) = (v4f){v0[0] + gate_b[0], v0[1] + gate_b[1], v0[2] + gate_b[2], v0[3] + gate_b[3]};
;                         *(v4f*)(mo + 4) = (v4f){v0[4] + gate_b[4], v0[5] + gate_b[5], v0[6] + gate_b[6], v0[7] + gate_b[7]};
;                     }
.LBB0_1166:
	s_andn2_b64 vcc, exec, s[22:23]
	s_cbranch_vccnz .LBB0_1170
	s_and_saveexec_b64 s[94:95], s[84:85]
	s_cbranch_execz .LBB0_1169
	s_nop 1
	v_lshlrev_b64 v[152:153], 5, v[188:189]
	v_lshl_add_u64 v[152:153], s[14:15], 0, v[152:153]
	v_pk_add_f32 v[136:137], v[148:149], v[222:223]
	v_pk_add_f32 v[138:139], v[140:141], v[224:225]
	global_store_dwordx4 v[152:153], v[136:139], off
	s_nop 1
	v_pk_add_f32 v[136:137], v[132:133], v[226:227]
	v_pk_add_f32 v[138:139], v[128:129], v[228:229]
	global_store_dwordx4 v[152:153], v[136:139], off offset:16

;     __device__ __forceinline__ void operator()(const f32x4 (&acc)[2][2][4][2], const Unit& u, int wr, int wc, int, int) const {
;     ...
;                     if (wc == 0 && fq == 0) {
;                         float* mo = mif + (size_t)row * 8;
;                         *(v4f*)(mo) = (v4f){v0[0] + gate_b[0], v0[1] + gate_b[1], v0[2] + gate_b[2], v0[3] + gate_b[3]};
;                         *(v4f*)(mo + 4) = (v4f){v0[4] + gate_b[4], v0[5] + gate_b[5], v0[6] + gate_b[6], v0[7] + gate_b[7]};
;                     }
.LBB0_1188:
	s_andn2_b64 vcc, exec, s[22:23]
	s_cbranch_vccnz .LBB0_1192
	s_and_saveexec_b64 s[94:95], s[84:85]
	s_cbranch_execz .LBB0_1191
	s_nop 1
	v_lshlrev_b64 v[120:121], 5, v[138:139]
	v_lshl_add_u64 v[120:121], s[14:15], 0, v[120:121]
	v_pk_add_f32 v[138:139], v[132:133], v[222:223]
	v_pk_add_f32 v[140:141], v[124:125], v[224:225]
	global_store_dwordx4 v[120:121], v[138:141], off
	s_nop 1
	v_pk_add_f32 v[138:139], v[116:117], v[226:227]
	v_pk_add_f32 v[140:141], v[112:113], v[228:229]
	global_store_dwordx4 v[120:121], v[138:141], off offset:16

;     __device__ __forceinline__ void operator()(const f32x4 (&acc)[2][2][4][2], const Unit& u, int wr, int wc, int, int) const {
;     ...
;                     if (wc == 0 && fq == 0) {
;                         float* mo = mif + (size_t)row * 8;
;                         *(v4f*)(mo) = (v4f){v0[0] + gate_b[0], v0[1] + gate_b[1], v0[2] + gate_b[2], v0[3] + gate_b[3]};
;                         *(v4f*)(mo + 4) = (v4f){v0[4] + gate_b[4], v0[5] + gate_b[5], v0[6] + gate_b[6], v0[7] + gate_b[7]};
;                     }
.LBB0_1206:
	s_andn2_b64 vcc, exec, s[22:23]
	s_cbranch_vccnz .LBB0_1210
	s_and_saveexec_b64 s[94:95], s[84:85]
	s_cbranch_execz .LBB0_1209
	s_nop 1
	v_lshlrev_b64 v[118:119], 5, v[136:137]
	v_lshl_add_u64 v[118:119], s[14:15], 0, v[118:119]
	v_pk_add_f32 v[104:105], v[112:113], v[222:223]
	v_pk_add_f32 v[106:107], v[108:109], v[224:225]
	global_store_dwordx4 v[118:119], v[104:107], off
	s_nop 1
	v_pk_add_f32 v[104:105], v[100:101], v[226:227]
	v_pk_add_f32 v[106:107], v[96:97], v[228:229]
	global_store_dwordx4 v[118:119], v[104:107], off offset:16

;     __device__ __forceinline__ void operator()(const f32x4 (&acc)[2][2][4][2], const Unit& u, int wr, int wc, int, int) const {
;     ...
;                     if (wc == 0 && fq == 0) {
;                         float* mo = mif + (size_t)row * 8;
;                         *(v4f*)(mo) = (v4f){v0[0] + gate_b[0], v0[1] + gate_b[1], v0[2] + gate_b[2], v0[3] + gate_b[3]};
;                         *(v4f*)(mo + 4) = (v4f){v0[4] + gate_b[4], v0[5] + gate_b[5], v0[6] + gate_b[6], v0[7] + gate_b[7]};
;                     }
.LBB0_1228:
	s_andn2_b64 vcc, exec, s[22:23]
	s_cbranch_vccnz .LBB0_1232
	s_and_saveexec_b64 s[94:95], s[84:85]
	s_cbranch_execz .LBB0_1231
	s_nop 1
	v_lshlrev_b64 v[88:89], 5, v[106:107]
	v_lshl_add_u64 v[88:89], s[14:15], 0, v[88:89]
	v_pk_add_f32 v[110:111], v[100:101], v[222:223]
	v_pk_add_f32 v[112:113], v[92:93], v[224:225]
	global_store_dwordx4 v[88:89], v[110:113], off
	s_nop 1
	v_pk_add_f32 v[110:111], v[84:85], v[226:227]
	v_pk_add_f32 v[112:113], v[80:81], v[228:229]
	global_store_dwordx4 v[88:89], v[110:113], off offset:16

;     __device__ __forceinline__ void operator()(const f32x4 (&acc)[2][2][4][2], const Unit& u, int wr, int wc, int, int) const {
;     ...
;                     if (wc == 0 && fq == 0) {
;                         float* mo = mif + (size_t)row * 8;
;                         *(v4f*)(mo) = (v4f){v0[0] + gate_b[0], v0[1] + gate_b[1], v0[2] + gate_b[2], v0[3] + gate_b[3]};
;                         *(v4f*)(mo + 4) = (v4f){v0[4] + gate_b[4], v0[5] + gate_b[5], v0[6] + gate_b[6], v0[7] + gate_b[7]};
;                     }
.LBB0_1246:
	s_andn2_b64 vcc, exec, s[22:23]
	s_cbranch_vccnz .LBB0_1250
	s_and_saveexec_b64 s[94:95], s[84:85]
	s_cbranch_execz .LBB0_1249
	s_nop 1
	v_lshlrev_b64 v[86:87], 5, v[104:105]
	v_lshl_add_u64 v[86:87], s[14:15], 0, v[86:87]
	v_pk_add_f32 v[72:73], v[80:81], v[222:223]
	v_pk_add_f32 v[74:75], v[76:77], v[224:225]
	global_store_dwordx4 v[86:87], v[72:75], off
	s_nop 1
	v_pk_add_f32 v[72:73], v[68:69], v[226:227]
	v_pk_add_f32 v[74:75], v[64:65], v[228:229]
	global_store_dwordx4 v[86:87], v[72:75], off offset:16

;     __device__ __forceinline__ void operator()(const f32x4 (&acc)[2][2][4][2], const Unit& u, int wr, int wc, int, int) const {
;     ...
;                     if (wc == 0 && fq == 0) {
;                         float* mo = mif + (size_t)row * 8;
;                         *(v4f*)(mo) = (v4f){v0[0] + gate_b[0], v0[1] + gate_b[1], v0[2] + gate_b[2], v0[3] + gate_b[3]};
;                         *(v4f*)(mo + 4) = (v4f){v0[4] + gate_b[4], v0[5] + gate_b[5], v0[6] + gate_b[6], v0[7] + gate_b[7]};
;                     }
.LBB0_1268:
	s_andn2_b64 vcc, exec, s[6:7]
	s_cbranch_vccnz .LBB0_1272
	s_and_saveexec_b64 s[6:7], s[84:85]
	s_cbranch_execz .LBB0_1271
	s_nop 1
	v_lshlrev_b64 v[40:41], 5, v[74:75]
	v_lshl_add_u64 v[40:41], s[14:15], 0, v[40:41]
	v_pk_add_f32 v[74:75], v[68:69], v[222:223]
	v_pk_add_f32 v[76:77], v[44:45], v[224:225]
	global_store_dwordx4 v[40:41], v[74:77], off
	s_nop 1
	v_pk_add_f32 v[74:75], v[36:37], v[226:227]
	v_pk_add_f32 v[76:77], v[28:29], v[228:229]
	global_store_dwordx4 v[40:41], v[74:77], off offset:16

;     __device__ __forceinline__ void operator()(const f32x4 (&acc)[2][2][4][2], const Unit& u, int wr, int wc, int, int) const {
;     ...
;                     if (wc == 0 && fq == 0) {
;                         float* mo = mif + (size_t)row * 8;
;                         *(v4f*)(mo) = (v4f){v0[0] + gate_b[0], v0[1] + gate_b[1], v0[2] + gate_b[2], v0[3] + gate_b[3]};
;                         *(v4f*)(mo + 4) = (v4f){v0[4] + gate_b[4], v0[5] + gate_b[5], v0[6] + gate_b[6], v0[7] + gate_b[7]};
;                     }
.LBB0_1286:
	s_andn2_b64 vcc, exec, s[6:7]
	s_cbranch_vccnz .LBB0_1290
	s_and_saveexec_b64 s[6:7], s[84:85]
	s_cbranch_execz .LBB0_1289
	s_nop 1
	v_lshlrev_b64 v[38:39], 5, v[72:73]
	v_lshl_add_u64 v[38:39], s[14:15], 0, v[38:39]
	v_pk_add_f32 v[8:9], v[28:29], v[222:223]
	v_pk_add_f32 v[10:11], v[12:13], v[224:225]
	global_store_dwordx4 v[38:39], v[8:11], off
	s_nop 1
	v_pk_add_f32 v[8:9], v[4:5], v[226:227]
	v_pk_add_f32 v[10:11], v[0:1], v[228:229]
	global_store_dwordx4 v[38:39], v[8:11], off offset:16
